# passC walk + flat->global + SB finalize batched gate loads + SB V-fragment reads hoisted
# speedup vs baseline: 1.0070x; 1.0049x over previous
; template <bool MASK>
; DI void sb_block(const LAS unsigned char* kb, const LAS unsigned char* vb, int koff, int s0, int tq, const bf16x8 (&qb)[4], f32x4 (&o)[8], float& R, int g, int r16) {
;     ...
;     for (int kt = 0; kt < 2; ++kt) { z[kt] = (f32x4){0.f, 0.f, 0.f, 0.f};
; #pragma unroll
;         for (int ks = 0; ks < 4; ++ks) { const bf16x8 a = *(const LAS bf16x8*)(kb + (koff + 16 * kt + r16) * 272 + (32 * ks + 8 * g) * 2); z[kt] = mfma16(a, qb[ks], z[kt]); } }
;     float suf[2][4], TT[2];
; #pragma unroll
;     for (int kt = 0; kt < 2; ++kt) {
;         float sp[4];
; #pragma unroll
;         for (int j = 0; j < 4; ++j) { const float zz = z[kt][j] * scl2; z[kt][j] = zz;
;             const float v = fmaxf(zz, 0.f) + __builtin_amdgcn_logf(1.f + __builtin_amdgcn_exp2f(-fabsf(zz)));
;             sp[j] = (!MASK || (s0 + 16 * kt + 4 * g + j < tq)) ? v : 0.f; }
;         const float s3 = sp[3], s2 = sp[2] + s3, s1 = sp[1] + s2, s0_ = sp[0] + s1;
;         const float o16 = __shfl_xor(s0_, 16), a2 = s0_ + o16, b2 = __shfl_xor(a2, 32);
;         const float E = ((g & 1) == 0 ? o16 : 0.f) + (g < 2 ? b2 : 0.f);
;         TT[kt] = a2 + b2; suf[kt][0] = s0_ + E; suf[kt][1] = s1 + E; suf[kt][2] = s2 + E; suf[kt][3] = s3 + E;
;     }
;     float base = R; float aw[2][4];
; #pragma unroll
;     ...
; #pragma unroll
;         for (int j = 0; j < 4; ++j) { const float v = __builtin_amdgcn_exp2f(z[kt][j] - (base + suf[kt][j])); aw[kt][j] = (!MASK || (s0 + 16 * kt + 4 * g + j < tq)) ? v : 0.f; }
;         base += TT[kt]; }
;     R = base;
;     u32x4 t; t.x = pk2(aw[0][0], aw[0][1]); t.y = pk2(aw[0][2], aw[0][3]); t.z = pk2(aw[1][0], aw[1][1]); t.w = pk2(aw[1][2], aw[1][3]); const bf16x8 bop = __builtin_bit_cast(bf16x8, t);
; #pragma unroll
;     for (int vt = 0; vt < 8; ++vt) { const LAS unsigned char* ap = vb + (16 * vt + r16) * 400 + (koff + 4 * g) * 2;
;         const bf16x8 a = cat4(*(const LAS s16x4*)ap, *(const LAS s16x4*)(ap + 32)); o[vt] = mfma16(a, bop, o[vt]); }
; DI void sb_phase(const Params& P, LAS unsigned char* lds) {
;     ...
;             if (s0 < 0) break;
;             if (s0 >= twmax) continue;
;             if (__all(R > SB_RDONE)) break;
;             if (s0 + 32 > twmax - 15) sb_block<true>(lds, lds + SB_VOFF, 32 * hb, s0, tq, qb, o, R, g, r16);
;             else sb_block<false>(lds, lds + SB_VOFF, 32 * hb, s0, tq, qb, o, R, g, r16); }
.LBB0_55:
	s_add_i32 s1, s64, 0x60
	s_cmp_lt_i32 s1, 0
	v_mov_b32_e32 v114, 33
	s_cbranch_scc1 .LBB0_65
	v_cmp_lt_i32_e32 vcc, s1, v0
	v_mov_b32_e32 v114, 35
	s_and_saveexec_b64 s[34:35], vcc
	s_cbranch_execz .LBB0_64
	v_cmp_lt_f32_e32 vcc, s97, v183
	s_cmp_eq_u64 vcc, exec
	s_mov_b32 s0, 33
	s_cbranch_scc1 .LBB0_63
	ds_read_b128 v[138:141], v148
	ds_read_b128 v[142:145], v148 offset:64
	ds_read_b128 v[134:137], v148 offset:128
	ds_read_b128 v[114:117], v148 offset:192
	ds_read_b128 v[130:133], v148 offset:4352
	ds_read_b128 v[126:129], v148 offset:4416
	ds_read_b128 v[122:125], v148 offset:4480
	ds_read_b128 v[118:121], v148 offset:4544
	v_add_u32_e32 v150, s68, v198
	v_cmp_le_i32_e32 vcc, s1, v146
	v_add_u32_e32 v161, 0xc800, v150
	v_add_u32_e32 v160, 0xe000, v150
	v_add_u32_e32 v159, 0xf800, v150
	v_add_u32_e32 v157, 0x11840, v150
	v_add_u32_e32 v158, 0x11860, v150
	v_add_u32_e32 v155, 0x13140, v150
	v_add_u32_e32 v156, 0x13160, v150
	v_add_u32_e32 v153, 0x14a40, v150
	v_add_u32_e32 v154, 0x14a60, v150
	v_add_u32_e32 v151, 0x16340, v150
	v_add_u32_e32 v152, 0x16360, v150
	v_add_u32_e32 v149, 0x17c40, v150
	v_add_u32_e32 v150, 0x17c60, v150
	s_and_saveexec_b64 s[0:1], vcc
	s_xor_b64 s[0:1], exec, s[0:1]
	s_cbranch_execz .LBB0_60
	s_waitcnt lgkmcnt(0)
	v_mfma_f32_16x16x32_bf16 v[138:141], v[138:141], v[110:113], 0
	s_mov_b32 s8, 0x3e0293ee
	v_mfma_f32_16x16x32_bf16 v[138:141], v[142:145], v[106:109], v[138:141]
	v_and_b32_e32 v143, 64, v231
	v_xor_b32_e32 v142, 16, v231
	v_add_u32_e32 v143, 64, v143
	v_mfma_f32_16x16x32_bf16 v[130:133], v[130:133], v[110:113], 0
	v_cmp_lt_i32_e32 vcc, v142, v143
	v_mfma_f32_16x16x32_bf16 v[134:137], v[134:137], v[102:105], v[138:141]
	v_mfma_f32_16x16x32_bf16 v[126:129], v[126:129], v[106:109], v[130:133]
	s_nop 1
	v_cndmask_b32_e32 v138, v231, v142, vcc
	v_lshlrev_b32_e32 v138, 2, v138
	v_xor_b32_e32 v139, 32, v231
	v_mfma_f32_16x16x32_bf16 v[114:117], v[114:117], v[98:101], v[134:137]
	v_cmp_lt_i32_e32 vcc, v139, v143
	v_mfma_f32_16x16x32_bf16 v[122:125], v[122:125], v[102:105], v[126:129]
	v_mfma_f32_16x16x32_bf16 v[118:121], v[118:121], v[98:101], v[122:125]
	ds_read2_b64 v[214:217], v161 offset0:168 offset1:172
	ds_read2_b64 v[218:221], v160 offset0:200 offset1:204
	ds_read2_b64 v[222:225], v159 offset0:232 offset1:236
	ds_read_b64 v[232:233], v157
	ds_read_b64 v[234:235], v158
	ds_read_b64 v[236:237], v155
	ds_read_b64 v[238:239], v156
	ds_read_b64 v[240:241], v153
	ds_read_b64 v[242:243], v154
	ds_read_b64 v[244:245], v151
	ds_read_b64 v[246:247], v152
	ds_read_b64 v[248:249], v149
	ds_read_b64 v[250:251], v150
	s_nop 4
	v_mul_f32_e32 v127, 0x3e0293ee, v117
	v_exp_f32_e64 v128, -|v127|
	v_mul_f32_e32 v135, 0x3e0293ee, v116
	v_exp_f32_e64 v141, -|v135|
	v_mul_f32_e32 v134, 0x3e0293ee, v115
	v_add_f32_e32 v123, 1.0, v128
	v_log_f32_e32 v124, v123
	v_mul_f32_e32 v123, 0x3e0293ee, v118
	v_exp_f32_e64 v125, -|v123|
	v_exp_f32_e64 v140, -|v134|
	v_max_f32_e32 v132, 0, v135
	v_add_f32_e32 v131, 1.0, v141
	v_max_f32_e32 v135, 0, v123
	v_mul_f32_e32 v123, 0x3e0293ee, v119
	v_add_f32_e32 v125, 1.0, v125
	v_log_f32_e32 v126, v131
	v_max_f32_e32 v122, 0, v127
	v_exp_f32_e64 v127, -|v123|
	v_log_f32_e32 v131, v125
	v_mul_f32_e32 v125, 0x3e0293ee, v120
	v_add_f32_e32 v140, 1.0, v140
	v_exp_f32_e64 v128, -|v125|
	v_mul_f32_e32 v129, 0x3e0293ee, v121
	v_log_f32_e32 v130, v140
	v_exp_f32_e64 v140, -|v129|
	v_max_f32_e32 v133, 0, v123
	v_add_f32_e32 v123, 1.0, v127
	v_log_f32_e32 v127, v123
	v_add_f32_e32 v123, 1.0, v128
	v_log_f32_e32 v123, v123
	v_add_f32_e32 v128, 1.0, v140
	v_log_f32_e32 v128, v128
	v_mul_f32_e32 v136, 0x3e0293ee, v114
	v_max_f32_e32 v125, 0, v125
	v_exp_f32_e64 v137, -|v136|
	v_add_f32_e32 v123, v125, v123
	v_max_f32_e32 v125, 0, v129
	v_add_f32_e32 v125, v125, v128
	v_max_f32_e32 v134, 0, v134
	v_pk_add_f32 v[126:127], v[132:133], v[126:127]
	v_pk_add_f32 v[122:123], v[122:123], v[124:125]
	v_pk_add_f32 v[128:129], v[134:135], v[130:131]
	v_pk_add_f32 v[126:127], v[126:127], v[122:123]
	v_add_f32_e32 v137, 1.0, v137
	v_pk_add_f32 v[128:129], v[128:129], v[126:127]
	v_log_f32_e32 v137, v137
	ds_bpermute_b32 v131, v138, v129
	v_max_f32_e32 v130, 0, v136
	v_cndmask_b32_e32 v124, v231, v139, vcc
	v_add_f32_e32 v130, v130, v137
	v_lshlrev_b32_e32 v124, 2, v124
	s_waitcnt lgkmcnt(0)
	v_pk_add_f32 v[132:133], v[128:129], v[130:131]
	ds_bpermute_b32 v134, v138, v132
	ds_bpermute_b32 v135, v124, v133
	s_waitcnt lgkmcnt(0)
	v_pk_add_f32 v[136:137], v[132:133], v[134:135]
	ds_bpermute_b32 v182, v124, v136
	v_cndmask_b32_e64 v124, 0, v134, s[36:37]
	s_waitcnt lgkmcnt(0)
	v_cndmask_b32_e64 v130, 0, v182, s[38:39]
	v_add_f32_e32 v124, v124, v130
	v_add_f32_e32 v130, v132, v124
	v_add_f32_e32 v128, v128, v124
	v_add_f32_e32 v132, v126, v124
	v_add_f32_e32 v122, v122, v124
	v_cndmask_b32_e64 v124, 0, v131, s[36:37]
	v_cndmask_b32_e64 v126, 0, v135, s[38:39]
	v_add_f32_e32 v124, v124, v126
	v_add_f32_e32 v126, v124, v129
	v_add_f32_e32 v127, v124, v127
	v_add_f32_e32 v123, v123, v124
	v_add_f32_e32 v124, v125, v124
	v_add_f32_e32 v125, v183, v126
	v_fma_f32 v118, v118, s8, -v125
	v_exp_f32_e32 v129, v118
	v_add_f32_e32 v118, v183, v127
	v_pk_add_f32 v[126:127], v[136:137], v[182:183]
	v_fma_f32 v118, v119, s8, -v118
	v_add_f32_e32 v119, v130, v127
	v_fma_f32 v114, v114, s8, -v119
	v_exp_f32_e32 v119, v114
	v_add_f32_e32 v114, v128, v127
	v_exp_f32_e32 v131, v118
	v_add_f32_e32 v118, v183, v123
	v_fma_f32 v114, v115, s8, -v114
	v_fma_f32 v118, v120, s8, -v118
	v_exp_f32_e32 v120, v114
	v_add_f32_e32 v114, v132, v127
	v_fma_f32 v114, v116, s8, -v114
	v_exp_f32_e32 v123, v114
	v_add_f32_e32 v114, v122, v127
	v_fma_f32 v122, v117, s8, -v114
	v_exp_f32_e32 v133, v118
	v_add_f32_e32 v118, v183, v124
	v_fma_f32 v118, v121, s8, -v118
	v_exp_f32_e32 v122, v122
	v_exp_f32_e32 v121, v118
	v_cvt_pk_bf16_f32 v118, v119, v120
	v_cvt_pk_bf16_f32 v120, v129, v131
	v_cvt_pk_bf16_f32 v119, v123, v122
	v_cvt_pk_bf16_f32 v121, v133, v121
	v_add_f32_e32 v183, v126, v127
	s_waitcnt lgkmcnt(0)
	s_nop 1
	v_mfma_f32_16x16x32_bf16 v[94:97], v[214:217], v[118:121], v[94:97]
	v_mfma_f32_16x16x32_bf16 v[90:93], v[218:221], v[118:121], v[90:93]
	v_mfma_f32_16x16x32_bf16 v[86:89], v[222:225], v[118:121], v[86:89]
	v_mfma_f32_16x16x32_bf16 v[82:85], v[232:235], v[118:121], v[82:85]
	v_mfma_f32_16x16x32_bf16 v[78:81], v[236:239], v[118:121], v[78:81]
	v_mfma_f32_16x16x32_bf16 v[70:73], v[244:247], v[118:121], v[70:73]
	v_mfma_f32_16x16x32_bf16 v[74:77], v[240:243], v[118:121], v[74:77]
	v_mfma_f32_16x16x32_bf16 v[34:37], v[248:251], v[118:121], v[34:37]
; #define LAS __attribute__((address_space(3)))
; DI unsigned pk2(float lo, float hi) { f32x2_t f = {lo, hi}; bf16x2_t v = __builtin_convertvector(f, bf16x2_t); return __builtin_bit_cast(unsigned, v); }
; DI f32x4 mfma16(bf16x8 a, bf16x8 b, f32x4 c) { return __builtin_amdgcn_mfma_f32_16x16x32_bf16(a, b, c, 0, 0, 0); }
; DI bf16x8 cat4(s16x4 lo, s16x4 hi) { return __builtin_shufflevector(lo, hi, 0, 1, 2, 3, 4, 5, 6, 7); }
; template <bool MASK>
; DI void sb_block(const LAS unsigned char* kb, const LAS unsigned char* vb, int koff, int s0, int tq, const bf16x8 (&qb)[4], f32x4 (&o)[8], float& R, int g, int r16) {
;     ...
;     for (int kt = 0; kt < 2; ++kt) {
;         float sp[4];
; #pragma unroll
;         for (int j = 0; j < 4; ++j) { const float zz = z[kt][j] * scl2; z[kt][j] = zz;
;             const float v = fmaxf(zz, 0.f) + __builtin_amdgcn_logf(1.f + __builtin_amdgcn_exp2f(-fabsf(zz)));
;             sp[j] = (!MASK || (s0 + 16 * kt + 4 * g + j < tq)) ? v : 0.f; }
;         const float s3 = sp[3], s2 = sp[2] + s3, s1 = sp[1] + s2, s0_ = sp[0] + s1;
;         const float o16 = __shfl_xor(s0_, 16), a2 = s0_ + o16, b2 = __shfl_xor(a2, 32);
;         const float E = ((g & 1) == 0 ? o16 : 0.f) + (g < 2 ? b2 : 0.f);
;         TT[kt] = a2 + b2; suf[kt][0] = s0_ + E; suf[kt][1] = s1 + E; suf[kt][2] = s2 + E; suf[kt][3] = s3 + E;
;     }
;     float base = R; float aw[2][4];
; #pragma unroll
;     ...
; #pragma unroll
;         for (int j = 0; j < 4; ++j) { const float v = __builtin_amdgcn_exp2f(z[kt][j] - (base + suf[kt][j])); aw[kt][j] = (!MASK || (s0 + 16 * kt + 4 * g + j < tq)) ? v : 0.f; }
;         base += TT[kt]; }
;     R = base;
;     u32x4 t; t.x = pk2(aw[0][0], aw[0][1]); t.y = pk2(aw[0][2], aw[0][3]); t.z = pk2(aw[1][0], aw[1][1]); t.w = pk2(aw[1][2], aw[1][3]); const bf16x8 bop = __builtin_bit_cast(bf16x8, t);
; #pragma unroll
;     for (int vt = 0; vt < 8; ++vt) { const LAS unsigned char* ap = vb + (16 * vt + r16) * 400 + (koff + 4 * g) * 2;
;         const bf16x8 a = cat4(*(const LAS s16x4*)ap, *(const LAS s16x4*)(ap + 32)); o[vt] = mfma16(a, bop, o[vt]); }
.LBB0_60:
	s_andn2_saveexec_b64 s[56:57], s[0:1]
	s_cbranch_execz .LBB0_62
	s_waitcnt lgkmcnt(0)
	v_mfma_f32_16x16x32_bf16 v[130:133], v[130:133], v[110:113], 0
	s_mov_b32 s8, 0x3e0293ee
	v_mfma_f32_16x16x32_bf16 v[138:141], v[138:141], v[110:113], 0
	v_mfma_f32_16x16x32_bf16 v[126:129], v[126:129], v[106:109], v[130:133]
	v_mfma_f32_16x16x32_bf16 v[138:141], v[142:145], v[106:109], v[138:141]
	v_mfma_f32_16x16x32_bf16 v[122:125], v[122:125], v[102:105], v[126:129]
	v_mfma_f32_16x16x32_bf16 v[134:137], v[134:137], v[102:105], v[138:141]
	v_mfma_f32_16x16x32_bf16 v[118:121], v[118:121], v[98:101], v[122:125]
	s_nop 5
	v_and_b32_e32 v124, 64, v231
	v_xor_b32_e32 v122, 16, v231
	v_add_u32_e32 v124, 64, v124
	v_cmp_lt_i32_e32 vcc, v122, v124
	v_mfma_f32_16x16x32_bf16 v[114:117], v[114:117], v[98:101], v[134:137]
	ds_read2_b64 v[214:217], v161 offset0:168 offset1:172
	ds_read2_b64 v[218:221], v160 offset0:200 offset1:204
	ds_read2_b64 v[222:225], v159 offset0:232 offset1:236
	ds_read_b64 v[232:233], v157
	ds_read_b64 v[234:235], v158
	ds_read_b64 v[236:237], v155
	ds_read_b64 v[238:239], v156
	ds_read_b64 v[240:241], v153
	ds_read_b64 v[242:243], v154
	ds_read_b64 v[244:245], v151
	ds_read_b64 v[246:247], v152
	ds_read_b64 v[248:249], v149
	ds_read_b64 v[250:251], v150
	v_mul_f32_e32 v133, 0x3e0293ee, v120
	v_cndmask_b32_e32 v122, v231, v122, vcc
	v_add_u32_e32 v123, s64, v178
	v_lshlrev_b32_e32 v135, 2, v122
	v_xor_b32_e32 v122, 32, v231
	v_cmp_lt_i32_e32 vcc, v122, v124
	s_nop 1
	v_mul_f32_e32 v125, 0x3e0293ee, v115
	v_max_f32_e32 v137, 0, v133
	v_cndmask_b32_e32 v122, v231, v122, vcc
	v_lshlrev_b32_e32 v136, 2, v122
	v_mul_f32_e32 v122, 0x3e0293ee, v114
	v_max_f32_e32 v124, 0, v122
	v_exp_f32_e64 v122, -|v122|
	v_exp_f32_e64 v133, -|v133|
	v_mul_f32_e32 v131, 0x3e0293ee, v119
	v_max_f32_e32 v129, 0, v131
	v_add_f32_e32 v122, 1.0, v122
	v_log_f32_e32 v122, v122
	v_add_f32_e32 v133, 1.0, v133
	v_log_f32_e32 v133, v133
	v_exp_f32_e64 v131, -|v131|
	v_add_f32_e32 v122, v124, v122
	v_max_f32_e32 v124, 0, v125
	v_exp_f32_e64 v125, -|v125|
	v_add_f32_e32 v133, v137, v133
	v_add_u32_e32 v137, 0x72, v123
	v_cmp_lt_i32_e64 s[44:45], v137, v184
	v_add_f32_e32 v125, 1.0, v125
	v_log_f32_e32 v126, v125
	v_mul_f32_e32 v125, 0x3e0293ee, v116
	v_max_f32_e32 v128, 0, v125
	v_exp_f32_e64 v125, -|v125|
	v_mul_f32_e32 v137, 0x3e0293ee, v121
	v_max_f32_e32 v138, 0, v137
	v_exp_f32_e64 v137, -|v137|
	v_add_f32_e32 v125, 1.0, v125
	v_log_f32_e32 v130, v125
	v_mul_f32_e32 v125, 0x3e0293ee, v117
	v_max_f32_e32 v127, 0, v125
	v_exp_f32_e64 v125, -|v125|
	v_add_f32_e32 v131, 1.0, v131
	v_add_f32_e32 v137, 1.0, v137
	v_log_f32_e32 v131, v131
	v_add_f32_e32 v125, 1.0, v125
	v_log_f32_e32 v125, v125
	v_log_f32_e32 v137, v137
	v_add_u32_e32 v134, 0x60, v123
	v_cndmask_b32_e64 v133, 0, v133, s[44:45]
	v_add_f32_e32 v125, v127, v125
	v_add_u32_e32 v127, 0x63, v123
	v_cmp_lt_i32_e64 s[0:1], v127, v184
	v_mul_f32_e32 v127, 0x3e0293ee, v118
	v_add_u32_e32 v123, 0x73, v123
	v_cndmask_b32_e64 v132, 0, v125, s[0:1]
	v_max_f32_e32 v125, 0, v127
	v_exp_f32_e64 v127, -|v127|
	v_cmp_lt_i32_e64 s[50:51], v123, v184
	v_or_b32_e32 v123, 16, v134
	v_add_f32_e32 v137, v138, v137
	v_add_f32_e32 v127, 1.0, v127
	v_log_f32_e32 v127, v127
	v_cmp_lt_i32_e64 s[52:53], v123, v147
	v_or_b32_e32 v123, 17, v134
	v_cndmask_b32_e64 v137, 0, v137, s[50:51]
	v_pk_add_f32 v[124:125], v[124:125], v[126:127]
	v_pk_add_f32 v[126:127], v[128:129], v[130:131]
	v_or_b32_e32 v128, 2, v134
	v_or_b32_e32 v138, 1, v134
	v_cmp_lt_i32_e64 s[48:49], v128, v184
	v_cmp_lt_i32_e64 s[54:55], v123, v147
	v_add_f32_e32 v133, v133, v137
	v_cmp_lt_i32_e64 s[46:47], v138, v184
	v_cndmask_b32_e64 v127, 0, v127, s[54:55]
	v_cndmask_b32_e64 v126, 0, v126, s[48:49]
	v_cndmask_b32_e64 v125, 0, v125, s[52:53]
	v_cndmask_b32_e64 v124, 0, v124, s[46:47]
	v_pk_add_f32 v[126:127], v[126:127], v[132:133]
	v_cmp_lt_i32_e32 vcc, v134, v184
	v_pk_add_f32 v[124:125], v[124:125], v[126:127]
	ds_bpermute_b32 v123, v135, v125
	v_cndmask_b32_e32 v122, 0, v122, vcc
	s_waitcnt lgkmcnt(0)
	v_pk_add_f32 v[128:129], v[122:123], v[124:125]
	ds_bpermute_b32 v130, v135, v128
	ds_bpermute_b32 v131, v136, v129
	v_cndmask_b32_e64 v123, 0, v123, s[36:37]
	s_waitcnt lgkmcnt(0)
	v_cndmask_b32_e64 v122, 0, v130, s[36:37]
	v_pk_add_f32 v[134:135], v[128:129], v[130:131]
	ds_bpermute_b32 v182, v136, v134
	s_waitcnt lgkmcnt(0)
	v_cndmask_b32_e64 v129, 0, v182, s[38:39]
	v_add_f32_e32 v122, v122, v129
	v_cndmask_b32_e64 v129, 0, v131, s[38:39]
	v_add_f32_e32 v123, v123, v129
	v_add_f32_e32 v125, v123, v125
	v_add_f32_e32 v125, v183, v125
	v_fma_f32 v118, v118, s8, -v125
	v_exp_f32_e32 v118, v118
	v_add_f32_e32 v127, v123, v127
	v_add_f32_e32 v129, v123, v133
	v_add_f32_e32 v123, v137, v123
	v_cndmask_b32_e64 v125, 0, v118, s[52:53]
	v_add_f32_e32 v118, v183, v127
	v_fma_f32 v118, v119, s8, -v118
	v_exp_f32_e32 v118, v118
	v_add_f32_e32 v128, v122, v128
	v_add_f32_e32 v124, v124, v122
	v_add_f32_e32 v126, v126, v122
	v_cndmask_b32_e64 v127, 0, v118, s[54:55]
	v_add_f32_e32 v118, v183, v129
	v_fma_f32 v118, v120, s8, -v118
	v_exp_f32_e32 v118, v118
	v_add_f32_e32 v122, v132, v122
	v_readlane_b32 s54, v254, 46
	v_readlane_b32 s55, v254, 47
	v_cndmask_b32_e64 v120, 0, v118, s[44:45]
	v_add_f32_e32 v118, v183, v123
	v_fma_f32 v118, v121, s8, -v118
	v_exp_f32_e32 v118, v118
	s_nop 0
	v_cndmask_b32_e64 v121, 0, v118, s[50:51]
	v_pk_add_f32 v[118:119], v[134:135], v[182:183]
	s_nop 0
	v_add_f32_e32 v123, v128, v119
	v_fma_f32 v114, v114, s8, -v123
	v_add_f32_e32 v123, v124, v119
	v_fma_f32 v115, v115, s8, -v123
	v_add_f32_e32 v123, v126, v119
	v_add_f32_e32 v122, v122, v119
	v_fma_f32 v116, v116, s8, -v123
	v_fma_f32 v117, v117, s8, -v122
	v_exp_f32_e32 v114, v114
	v_exp_f32_e32 v115, v115
	v_exp_f32_e32 v116, v116
	v_exp_f32_e32 v117, v117
	v_cndmask_b32_e32 v114, 0, v114, vcc
	v_cndmask_b32_e64 v115, 0, v115, s[46:47]
	v_cndmask_b32_e64 v116, 0, v116, s[48:49]
	v_cndmask_b32_e64 v117, 0, v117, s[0:1]
	v_add_f32_e32 v183, v118, v119
	v_cvt_pk_bf16_f32 v114, v114, v115
	v_cvt_pk_bf16_f32 v115, v116, v117
	v_cvt_pk_bf16_f32 v117, v120, v121
	v_cvt_pk_bf16_f32 v116, v125, v127
	s_waitcnt lgkmcnt(0)
	s_nop 1
	v_mfma_f32_16x16x32_bf16 v[94:97], v[214:217], v[114:117], v[94:97]
	v_mfma_f32_16x16x32_bf16 v[90:93], v[218:221], v[114:117], v[90:93]
	v_mfma_f32_16x16x32_bf16 v[86:89], v[222:225], v[114:117], v[86:89]
	v_mfma_f32_16x16x32_bf16 v[82:85], v[232:235], v[114:117], v[82:85]
	v_mfma_f32_16x16x32_bf16 v[78:81], v[236:239], v[114:117], v[78:81]
	v_mfma_f32_16x16x32_bf16 v[74:77], v[240:243], v[114:117], v[74:77]
	v_mfma_f32_16x16x32_bf16 v[70:73], v[244:247], v[114:117], v[70:73]
	v_mfma_f32_16x16x32_bf16 v[34:37], v[248:251], v[114:117], v[34:37]
